# phase 8 (ff2 L0) full tiles use the XCD-pair same-round mapping with recent-panels-first round order (as phase 16) instead of the panel^8 swap
# speedup vs baseline: 1.0101x; 1.0036x over previous
.LBB0_368:
	s_lshl_b32 s20, s85, 3
	v_cvt_f32_u32_e32 v0, s20
	s_sub_i32 s29, 0, s20
	s_ashr_i32 s6, s6, 3
	s_add_i32 s6, s27, s6
	v_rcp_iflag_f32_e32 v0, v0
	s_abs_i32 s27, s6
	s_ashr_i32 s26, s6, 31
	v_mul_f32_e32 v0, 0x4f7ffffe, v0
	v_cvt_u32_f32_e32 v0, v0
	s_nop 0
	v_readfirstlane_b32 s31, v0
	s_mul_i32 s29, s29, s31
	s_mul_hi_u32 s29, s31, s29
	s_add_i32 s31, s31, s29
	s_mul_hi_u32 s29, s27, s31
	s_mul_i32 s31, s29, s20
	s_sub_i32 s27, s27, s31
	s_add_i32 s31, s29, 1
	s_sub_i32 s38, s27, s20
	s_cmp_ge_u32 s27, s20
	s_cselect_b32 s29, s31, s29
	s_cselect_b32 s27, s38, s27
	s_add_i32 s31, s29, 1
	s_cmp_ge_u32 s27, s20
	s_cselect_b32 s27, s31, s29
	s_xor_b32 s27, s27, s26
	s_sub_i32 s26, s27, s26
	s_lshl_b32 s27, s26, 3
	s_sub_i32 s29, s92, s27
	s_min_i32 s29, s29, 8
	s_abs_i32 s31, s29
	v_cvt_f32_u32_e32 v0, s31
	s_sub_i32 s38, 0, s31
	s_mul_i32 s26, s26, s20
	s_sub_i32 s20, s6, s26
	v_rcp_iflag_f32_e32 v0, v0
	s_abs_i32 s26, s20
	s_xor_b32 s6, s20, s29
	s_ashr_i32 s6, s6, 31
	v_mul_f32_e32 v0, 0x4f7ffffe, v0
	v_cvt_u32_f32_e32 v0, v0
	s_nop 0
	v_readfirstlane_b32 s39, v0
	s_mul_i32 s38, s38, s39
	s_mul_hi_u32 s38, s39, s38
	s_add_i32 s39, s39, s38
	s_mul_hi_u32 s38, s26, s39
	v_cvt_f32_ubyte0_e32 v0, s88
	s_mul_i32 s39, s38, s31
	v_rcp_iflag_f32_e32 v0, v0
	s_sub_i32 s26, s26, s39
	s_add_i32 s39, s38, 1
	s_sub_i32 s42, s26, s31
	s_cmp_ge_u32 s26, s31
	s_cselect_b32 s38, s39, s38
	v_mul_f32_e32 v0, 0x4f7ffffe, v0
	s_cselect_b32 s26, s42, s26
	s_add_i32 s39, s38, 1
	v_cvt_u32_f32_e32 v0, v0
	s_cmp_ge_u32 s26, s31
	s_cselect_b32 s26, s39, s38
	s_xor_b32 s26, s26, s6
	s_sub_i32 s6, s26, s6
	v_readfirstlane_b32 s31, v0
	v_cvt_f32_u32_e32 v0, s85
	s_mul_i32 s26, s6, s29
	s_sub_i32 s29, 0, s88
	s_mul_i32 s29, s29, s31
	s_sub_i32 s20, s20, s26
	s_mul_hi_u32 s29, s31, s29
	s_add_i32 s20, s20, s27
	s_abs_i32 s27, s2
	s_add_i32 s31, s31, s29
	v_rcp_iflag_f32_e32 v0, v0
	s_mul_hi_u32 s29, s27, s31
	s_mul_i32 s31, s29, s88
	s_sub_i32 s27, s27, s31
	s_ashr_i32 s26, s2, 31
	s_add_i32 s31, s29, 1
	s_sub_i32 s38, s27, s88
	v_mul_f32_e32 v0, 0x4f7ffffe, v0
	s_cmp_ge_u32 s27, s88
	v_cvt_u32_f32_e32 v0, v0
	s_cselect_b32 s29, s31, s29
	s_cselect_b32 s27, s38, s27
	s_add_i32 s31, s29, 1
	s_cmp_ge_u32 s27, s88
	s_cselect_b32 s27, s31, s29
	s_sub_i32 s31, 0, s85
	v_readfirstlane_b32 s38, v0
	s_xor_b32 s27, s27, s26
	s_mul_i32 s31, s31, s38
	s_sub_i32 s26, s27, s26
	s_mul_hi_u32 s31, s38, s31
	s_abs_i32 s29, s26
	s_add_i32 s38, s38, s31
	s_mul_hi_u32 s31, s29, s38
	s_mul_i32 s38, s31, s85
	s_sub_i32 s29, s29, s38
	s_ashr_i32 s27, s26, 31
	s_add_i32 s38, s31, 1
	s_sub_i32 s39, s29, s85
	s_cmp_ge_u32 s29, s85
	s_cselect_b32 s31, s38, s31
	s_cselect_b32 s29, s39, s29
	s_add_i32 s38, s31, 1
	s_cmp_ge_u32 s29, s85
	s_cselect_b32 s29, s38, s31
	s_xor_b32 s29, s29, s27
	s_sub_i32 s27, s29, s27
	s_add_i32 s29, s27, s89
	s_mul_i32 s27, s27, s85
	s_sub_i32 s31, s26, s27
	s_mul_i32 s26, s26, s88
	s_sub_i32 s2, s2, s26
	s_mul_i32 s2, s90, s2
	s_lshl_b32 s2, s2, 6
	s_and_b64 s[26:27], s[36:37], exec
	v_readlane_b32 s38, v254, 58
	s_cselect_b32 s77, s20, s29
	s_cselect_b32 s76, s6, s31
	s_cselect_b32 s42, 0, s2
	s_cselect_b32 s6, s93, s90
	v_readlane_b32 s39, v254, 59
	s_cmp_eq_u32 s12, 8
	s_cbranch_scc1 .Lfn_rmY
	s_cmp_eq_u32 s12, 16
	s_cbranch_scc0 .Lfn_rm0
.Lfn_rmY:
	s_and_b32 s26, s84, 7
	s_lshr_b32 s27, s26, 1
	s_lshl_b32 s27, s27, 5
	s_add_i32 s27, s27, 8
	s_and_b32 s77, s77, 7
	s_add_i32 s77, s77, s27
	s_and_b32 s26, s26, 1
	s_lshl_b32 s26, s26, 2
	s_and_b32 s76, s76, 3
	s_add_i32 s76, s76, s26

.LBB0_381:
	s_ashr_i32 s3, s3, 3
	s_add_i32 s3, s57, s3
	s_abs_i32 s57, s3
	s_mul_hi_u32 s70, s57, s78
	s_mul_i32 s71, s70, s2
	s_sub_i32 s57, s57, s71
	s_ashr_i32 s7, s3, 31
	s_add_i32 s71, s70, 1
	s_sub_i32 s72, s57, s2
	s_cmp_ge_u32 s57, s2
	s_cselect_b32 s70, s71, s70
	s_cselect_b32 s57, s72, s57
	s_add_i32 s71, s70, 1
	s_cmp_ge_u32 s57, s2
	s_cselect_b32 s57, s71, s70
	s_xor_b32 s57, s57, s7
	s_sub_i32 s7, s57, s7
	s_lshl_b32 s57, s7, 3
	s_sub_i32 s70, s92, s57
	s_min_i32 s70, s70, 8
	s_abs_i32 s71, s70
	v_cvt_f32_u32_e32 v0, s71
	s_sub_i32 s73, 0, s71
	s_mul_i32 s7, s7, s2
	s_sub_i32 s3, s3, s7
	v_rcp_iflag_f32_e32 v0, v0
	s_abs_i32 s7, s3
	s_xor_b32 s72, s3, s70
	s_ashr_i32 s72, s72, 31
	v_mul_f32_e32 v0, 0x4f7ffffe, v0
	v_cvt_u32_f32_e32 v0, v0
	s_nop 0
	v_readfirstlane_b32 s74, v0
	s_mul_i32 s73, s73, s74
	s_mul_hi_u32 s73, s74, s73
	s_add_i32 s74, s74, s73
	s_mul_hi_u32 s73, s7, s74
	s_mul_i32 s74, s73, s71
	s_sub_i32 s7, s7, s74
	s_add_i32 s74, s73, 1
	s_sub_i32 s75, s7, s71
	s_cmp_ge_u32 s7, s71
	s_cselect_b32 s73, s74, s73
	s_cselect_b32 s7, s75, s7
	s_add_i32 s74, s73, 1
	s_cmp_ge_u32 s7, s71
	s_cselect_b32 s7, s74, s73
	s_xor_b32 s7, s7, s72
	s_sub_i32 s7, s7, s72
	s_mul_i32 s70, s7, s70
	s_sub_i32 s3, s3, s70
	s_abs_i32 s70, s43
	s_mul_hi_u32 s71, s70, s30
	s_mul_i32 s72, s71, s88
	s_sub_i32 s70, s70, s72
	s_add_i32 s3, s3, s57
	s_ashr_i32 s57, s43, 31
	s_add_i32 s72, s71, 1
	s_sub_i32 s73, s70, s88
	s_cmp_ge_u32 s70, s88
	s_cselect_b32 s71, s72, s71
	s_cselect_b32 s70, s73, s70
	s_add_i32 s72, s71, 1
	s_cmp_ge_u32 s70, s88
	s_cselect_b32 s70, s72, s71
	s_xor_b32 s70, s70, s57
	s_sub_i32 s57, s70, s57
	s_abs_i32 s71, s57
	s_mul_hi_u32 s72, s71, s31
	s_mul_i32 s73, s72, s85
	s_sub_i32 s71, s71, s73
	s_ashr_i32 s70, s57, 31
	s_add_i32 s73, s72, 1
	s_sub_i32 s74, s71, s85
	s_cmp_ge_u32 s71, s85
	s_cselect_b32 s72, s73, s72
	s_cselect_b32 s71, s74, s71
	s_add_i32 s73, s72, 1
	s_cmp_ge_u32 s71, s85
	s_cselect_b32 s71, s73, s72
	s_xor_b32 s71, s71, s70
	s_sub_i32 s70, s71, s70
	s_add_i32 s71, s70, s89
	s_mul_i32 s70, s70, s85
	s_sub_i32 s70, s57, s70
	s_mul_i32 s57, s57, s88
	s_sub_i32 s43, s43, s57
	v_readlane_b32 s57, v252, 9
	s_mul_i32 s43, s57, s43
	s_and_b64 s[0:1], s[0:1], exec
	s_cselect_b32 s57, s3, s71
	s_cselect_b32 s7, s7, s70
	s_cselect_b32 s70, 0, s43
	s_cselect_b32 s3, s93, s90
	s_cbranch_scc0 .Lmo_1
	s_cmp_eq_u32 s12, 8
	s_cbranch_scc1 .Lfn_rmX

.Lfn_rmX:
	s_and_b32 s71, s84, 7
	s_lshr_b32 s72, s71, 1
	s_lshl_b32 s72, s72, 2
	s_lshl_b32 s73, s52, 1
	s_add_i32 s73, s73, 1
	s_cmp_ge_u32 s73, 5
	s_cselect_b32 s74, 5, 0
	s_sub_i32 s73, s73, s74
	s_add_i32 s72, s72, s73
	s_lshl_b32 s72, s72, 3
	s_and_b32 s57, s57, 7
	s_add_i32 s57, s57, s72
	s_and_b32 s71, s71, 1
	s_lshl_b32 s71, s71, 2
	s_and_b32 s7, s7, 3
	s_add_i32 s7, s7, s71
